# P8/P18 epilogue stores plain instead of sc1 write-through (experiment)
# speedup vs baseline: 1.0099x; 1.0021x over previous
; __device__ __forceinline__ unsigned cvt_pk_bf16(float lo, float hi) { unsigned r; asm volatile("v_cvt_pk_bf16_f32 %0, %1, %2" : "=v"(r) : "v"(lo), "v"(hi)); return r; }
;     __device__ __forceinline__ void operator()(const f32x4 (&acc)[2][2][4][2], const Unit& u, int wr, int wc, int fr, int fq, int, const float (&rsv_)[8]) const {
;     ...
;             for (int m = 0; m < 4; ++m) rsv[ai][m] = ss ? rsqrtf(rsv_[ai * 4 + m] * (1.f / 2048.f) + EPS) : 1.f;
; #pragma unroll
;         for (int ai = 0; ai < 2; ++ai)
; #pragma unroll
;             for (int m = 0; m < 4; ++m) { bf16_t* rowp = base + (size_t)(row0 + ai * HALF + m * 16) * ldc + col0;
;                 const float rs = rsv[ai][m];
; #pragma unroll
;                 for (int bj = 0; bj < 2; ++bj) { f32x4 v0 = acc[ai][bj][m][0] * rs, v1 = acc[ai][bj][m][1] * rs;
;                     if (ACT == 1) {
; #pragma unroll
;                         for (int j = 0; j < 4; ++j) { const float a = fmaxf(v0[j], 0.f), b = fmaxf(v1[j], 0.f); v0[j] = a * a; v1[j] = b * b; } }
;                     if (ACT == 2) { if (act2) {
; #pragma unroll
;                         for (int j = 0; j < 4; ++j) { float x = v0[j]; float z = 0.7978845608028654f * (x + 0.044715f * x * x * x); v0[j] = x / (1.f + __expf(-2.f * z));
;                                                       x = v1[j]; z = 0.7978845608028654f * (x + 0.044715f * x * x * x); v1[j] = x / (1.f + __expf(-2.f * z)); } } }
;                     u32x4 w; w.x = cvt_pk_bf16(v0[0], v0[1]); w.y = cvt_pk_bf16(v0[2], v0[3]); w.z = cvt_pk_bf16(v1[0], v1[1]); w.w = cvt_pk_bf16(v1[2], v1[3]);
;                     { u32x4* dp_ = (u32x4*)(rowp + bj * HALF); asm volatile("global_store_dwordx4 %0, %1, off sc1\n\ts_nop 1" :: "v"(dp_), "v"(w) : "memory"); } } }
.LBB0_931:
	s_waitcnt vmcnt(0)
	v_fmamk_f32 v166, v166, 0x3a000000, v157
	v_mul_f32_e32 v167, 0x4b800000, v166
	v_cmp_gt_f32_e32 vcc, s65, v166
	v_fmamk_f32 v154, v154, 0x3a000000, v157
	v_cmp_gt_f32_e64 s[4:5], s65, v154
	v_cndmask_b32_e32 v166, v166, v167, vcc
	v_rsq_f32_e32 v166, v166
	v_mul_f32_e32 v167, 0x4b800000, v154
	v_cndmask_b32_e64 v154, v154, v167, s[4:5]
	v_fmamk_f32 v152, v152, 0x3a000000, v157
	v_mul_f32_e32 v167, 0x45800000, v166
	v_cndmask_b32_e32 v166, v166, v167, vcc
	v_mul_f32_e32 v168, 0x4b800000, v152
	v_cmp_gt_f32_e32 vcc, s65, v152
	v_rsq_f32_e32 v154, v154
	v_fmamk_f32 v150, v150, 0x3a000000, v157
	v_cndmask_b32_e32 v152, v152, v168, vcc
	v_rsq_f32_e32 v152, v152
	v_mul_f32_e32 v167, 0x45800000, v154
	v_mul_f32_e32 v168, 0x4b800000, v150
	v_cmp_gt_f32_e64 s[8:9], s65, v150
	v_fmamk_f32 v148, v148, 0x3a000000, v157
	v_fmamk_f32 v146, v146, 0x3a000000, v157
	v_cndmask_b32_e64 v150, v150, v168, s[8:9]
	v_cndmask_b32_e64 v168, v154, v167, s[4:5]
	v_mul_f32_e32 v154, 0x45800000, v152
	v_cndmask_b32_e32 v170, v152, v154, vcc
	v_mul_f32_e32 v154, 0x4b800000, v148
	v_cmp_gt_f32_e32 vcc, s65, v148
	v_rsq_f32_e32 v150, v150
	v_cmp_gt_f32_e64 s[4:5], s65, v146
	v_cndmask_b32_e32 v148, v148, v154, vcc
	v_rsq_f32_e32 v148, v148
	v_mul_f32_e32 v152, 0x45800000, v150
	v_mul_f32_e32 v154, 0x4b800000, v146
	v_cndmask_b32_e64 v146, v146, v154, s[4:5]
	v_cndmask_b32_e64 v154, v150, v152, s[8:9]
	v_mul_f32_e32 v150, 0x45800000, v148
	v_fmamk_f32 v145, v145, 0x3a000000, v157
	v_cndmask_b32_e32 v152, v148, v150, vcc
	v_mul_f32_e32 v150, 0x4b800000, v145
	v_cmp_gt_f32_e32 vcc, s65, v145
	v_fmamk_f32 v144, v144, 0x3a000000, v157
	v_rsq_f32_e32 v146, v146
	v_cndmask_b32_e32 v145, v145, v150, vcc
	v_mul_f32_e32 v150, 0x4b800000, v144
	v_cmp_gt_f32_e64 s[8:9], s65, v144
	v_rsq_f32_e32 v145, v145
	v_mul_f32_e32 v148, 0x45800000, v146
	v_cndmask_b32_e64 v144, v144, v150, s[8:9]
	v_rsq_f32_e32 v144, v144
	v_cndmask_b32_e64 v150, v146, v148, s[4:5]
	v_mul_f32_e32 v146, 0x45800000, v145
	v_pk_mul_f32 v[120:121], v[166:167], v[120:121] op_sel_hi:[0,1]
	v_cndmask_b32_e32 v148, v145, v146, vcc
	v_mul_f32_e32 v145, 0x45800000, v144
	v_pk_mul_f32 v[124:125], v[166:167], v[124:125] op_sel_hi:[0,1]
	v_pk_mul_f32 v[122:123], v[166:167], v[122:123] op_sel_hi:[0,1]
	v_max_f32_e32 v120, 0, v120
	v_cndmask_b32_e64 v146, v144, v145, s[8:9]
	v_lshl_add_u32 v172, s52, 8, v147
	v_lshl_or_b32 v144, s66, 8, v151
	v_pk_mul_f32 v[126:127], v[166:167], v[126:127] op_sel_hi:[0,1]
	v_mul_f32_e32 v167, v120, v120
	v_max_f32_e32 v120, 0, v125
	v_max_f32_e32 v121, 0, v121
	v_max_f32_e32 v122, 0, v122
	v_ashrrev_i32_e32 v145, 31, v144
	v_ashrrev_i32_e32 v173, 31, v172
	v_max_f32_e32 v124, 0, v124
	v_mul_f32_e32 v120, v120, v120
	v_mul_f32_e32 v125, v121, v121
	v_max_f32_e32 v121, 0, v126
	v_mul_f32_e32 v126, v122, v122
	v_max_f32_e32 v122, 0, v127
	v_max_f32_e32 v123, 0, v123
	v_pk_mul_f32 v[114:115], v[166:167], v[114:115] op_sel_hi:[0,1]
	v_pk_mul_f32 v[112:113], v[166:167], v[112:113] op_sel_hi:[0,1]
	v_lshl_add_u64 v[174:175], v[144:145], 1, s[16:17]
	v_lshlrev_b64 v[144:145], 14, v[172:173]
	v_mul_f32_e32 v124, v124, v124
	v_mul_f32_e32 v121, v121, v121
	v_mul_f32_e32 v122, v122, v122
	v_mul_f32_e32 v123, v123, v123
	v_cvt_pk_bf16_f32 v120, v124, v120
	v_pk_mul_f32 v[118:119], v[166:167], v[118:119] op_sel_hi:[0,1]
	v_pk_mul_f32 v[116:117], v[166:167], v[116:117] op_sel_hi:[0,1]
	v_max_f32_e32 v112, 0, v112
	v_max_f32_e32 v113, 0, v113
	v_max_f32_e32 v114, 0, v114
	v_lshl_add_u64 v[144:145], v[174:175], 0, v[144:145]
	v_cvt_pk_bf16_f32 v121, v121, v122
	v_cvt_pk_bf16_f32 v122, v167, v125
	v_cvt_pk_bf16_f32 v123, v126, v123
	v_max_f32_e32 v116, 0, v116
	global_store_dwordx4 v[144:145], v[120:123], off
	s_nop 1
	v_mul_f32_e32 v120, v112, v112
	v_max_f32_e32 v112, 0, v117
	v_mul_f32_e32 v117, v113, v113
	v_max_f32_e32 v113, 0, v118
	v_mul_f32_e32 v118, v114, v114
	v_max_f32_e32 v114, 0, v119
	v_mul_f32_e32 v112, v112, v112
	v_mul_f32_e32 v113, v113, v113
	v_max_f32_e32 v115, 0, v115
	v_mul_f32_e32 v114, v114, v114
	v_pk_mul_f32 v[104:105], v[168:169], v[104:105] op_sel_hi:[0,1]
	v_mul_f32_e32 v116, v116, v116
	v_mul_f32_e32 v115, v115, v115
	v_cvt_pk_bf16_f32 v112, v116, v112
	v_cvt_pk_bf16_f32 v113, v113, v114
	v_cvt_pk_bf16_f32 v114, v120, v117
	v_pk_mul_f32 v[108:109], v[168:169], v[108:109] op_sel_hi:[0,1]
	v_pk_mul_f32 v[106:107], v[168:169], v[106:107] op_sel_hi:[0,1]
	v_max_f32_e32 v104, 0, v104
	v_cvt_pk_bf16_f32 v115, v118, v115
	v_lshl_add_u64 v[116:117], v[144:145], 0, s[22:23]
	global_store_dwordx4 v[116:117], v[112:115], off
	s_nop 1
	v_or_b32_e32 v112, 16, v172
	v_pk_mul_f32 v[110:111], v[168:169], v[110:111] op_sel_hi:[0,1]
	v_mul_f32_e32 v114, v104, v104
	v_max_f32_e32 v104, 0, v109
	v_max_f32_e32 v105, 0, v105
	v_max_f32_e32 v106, 0, v106
	v_ashrrev_i32_e32 v113, 31, v112
	v_max_f32_e32 v108, 0, v108
	v_mul_f32_e32 v104, v104, v104
	v_mul_f32_e32 v109, v105, v105
	v_max_f32_e32 v105, 0, v110
	v_mul_f32_e32 v110, v106, v106
	v_max_f32_e32 v106, 0, v111
	v_max_f32_e32 v107, 0, v107
	v_pk_mul_f32 v[98:99], v[168:169], v[98:99] op_sel_hi:[0,1]
	v_pk_mul_f32 v[96:97], v[168:169], v[96:97] op_sel_hi:[0,1]
	v_lshlrev_b64 v[112:113], 14, v[112:113]
	v_mul_f32_e32 v108, v108, v108
	v_mul_f32_e32 v105, v105, v105
	v_mul_f32_e32 v106, v106, v106
	v_mul_f32_e32 v107, v107, v107
	v_cvt_pk_bf16_f32 v104, v108, v104
	v_pk_mul_f32 v[102:103], v[168:169], v[102:103] op_sel_hi:[0,1]
	v_pk_mul_f32 v[100:101], v[168:169], v[100:101] op_sel_hi:[0,1]
	v_max_f32_e32 v96, 0, v96
	v_max_f32_e32 v97, 0, v97
	v_max_f32_e32 v98, 0, v98
	v_lshl_add_u64 v[112:113], v[174:175], 0, v[112:113]
; __device__ __forceinline__ unsigned cvt_pk_bf16(float lo, float hi) { unsigned r; asm volatile("v_cvt_pk_bf16_f32 %0, %1, %2" : "=v"(r) : "v"(lo), "v"(hi)); return r; }
;     __device__ __forceinline__ void operator()(const f32x4 (&acc)[2][2][4][2], const Unit& u, int wr, int wc, int fr, int fq, int, const float (&rsv_)[8]) const {
;     ...
;             for (int m = 0; m < 4; ++m) { bf16_t* rowp = base + (size_t)(row0 + ai * HALF + m * 16) * ldc + col0;
;                 const float rs = rsv[ai][m];
; #pragma unroll
;                 for (int bj = 0; bj < 2; ++bj) { f32x4 v0 = acc[ai][bj][m][0] * rs, v1 = acc[ai][bj][m][1] * rs;
;                     if (ACT == 1) {
; #pragma unroll
;                         for (int j = 0; j < 4; ++j) { const float a = fmaxf(v0[j], 0.f), b = fmaxf(v1[j], 0.f); v0[j] = a * a; v1[j] = b * b; } }
;                     if (ACT == 2) { if (act2) {
; #pragma unroll
;                         for (int j = 0; j < 4; ++j) { float x = v0[j]; float z = 0.7978845608028654f * (x + 0.044715f * x * x * x); v0[j] = x / (1.f + __expf(-2.f * z));
;                                                       x = v1[j]; z = 0.7978845608028654f * (x + 0.044715f * x * x * x); v1[j] = x / (1.f + __expf(-2.f * z)); } } }
;                     u32x4 w; w.x = cvt_pk_bf16(v0[0], v0[1]); w.y = cvt_pk_bf16(v0[2], v0[3]); w.z = cvt_pk_bf16(v1[0], v1[1]); w.w = cvt_pk_bf16(v1[2], v1[3]);
;                     { u32x4* dp_ = (u32x4*)(rowp + bj * HALF); asm volatile("global_store_dwordx4 %0, %1, off sc1\n\ts_nop 1" :: "v"(dp_), "v"(w) : "memory"); } } }
	v_cvt_pk_bf16_f32 v105, v105, v106
	v_cvt_pk_bf16_f32 v106, v114, v109
	v_cvt_pk_bf16_f32 v107, v110, v107
	v_max_f32_e32 v100, 0, v100
	global_store_dwordx4 v[112:113], v[104:107], off
	s_nop 1
	v_mul_f32_e32 v104, v96, v96
	v_max_f32_e32 v96, 0, v101
	v_mul_f32_e32 v101, v97, v97
	v_max_f32_e32 v97, 0, v102
	v_mul_f32_e32 v102, v98, v98
	v_max_f32_e32 v98, 0, v103
	v_mul_f32_e32 v96, v96, v96
	v_mul_f32_e32 v97, v97, v97
	v_max_f32_e32 v99, 0, v99
	v_mul_f32_e32 v98, v98, v98
	v_pk_mul_f32 v[88:89], v[170:171], v[88:89] op_sel_hi:[0,1]
	v_mul_f32_e32 v100, v100, v100
	v_mul_f32_e32 v99, v99, v99
	v_cvt_pk_bf16_f32 v96, v100, v96
	v_cvt_pk_bf16_f32 v97, v97, v98
	v_cvt_pk_bf16_f32 v98, v104, v101
	v_pk_mul_f32 v[92:93], v[170:171], v[92:93] op_sel_hi:[0,1]
	v_pk_mul_f32 v[90:91], v[170:171], v[90:91] op_sel_hi:[0,1]
	v_max_f32_e32 v88, 0, v88
	v_cvt_pk_bf16_f32 v99, v102, v99
	v_lshl_add_u64 v[100:101], v[112:113], 0, s[22:23]
	global_store_dwordx4 v[100:101], v[96:99], off
	s_nop 1
	v_or_b32_e32 v96, 32, v172
	v_pk_mul_f32 v[94:95], v[170:171], v[94:95] op_sel_hi:[0,1]
	v_mul_f32_e32 v98, v88, v88
	v_max_f32_e32 v88, 0, v93
	v_max_f32_e32 v89, 0, v89
	v_max_f32_e32 v90, 0, v90
	v_ashrrev_i32_e32 v97, 31, v96
	v_max_f32_e32 v92, 0, v92
	v_mul_f32_e32 v88, v88, v88
	v_mul_f32_e32 v93, v89, v89
	v_max_f32_e32 v89, 0, v94
	v_mul_f32_e32 v94, v90, v90
	v_max_f32_e32 v90, 0, v95
	v_max_f32_e32 v91, 0, v91
	v_pk_mul_f32 v[82:83], v[170:171], v[82:83] op_sel_hi:[0,1]
	v_pk_mul_f32 v[80:81], v[170:171], v[80:81] op_sel_hi:[0,1]
	v_lshlrev_b64 v[96:97], 14, v[96:97]
	v_mul_f32_e32 v92, v92, v92
	v_mul_f32_e32 v89, v89, v89
	v_mul_f32_e32 v90, v90, v90
	v_mul_f32_e32 v91, v91, v91
	v_cvt_pk_bf16_f32 v88, v92, v88
	v_pk_mul_f32 v[86:87], v[170:171], v[86:87] op_sel_hi:[0,1]
	v_pk_mul_f32 v[84:85], v[170:171], v[84:85] op_sel_hi:[0,1]
	v_max_f32_e32 v80, 0, v80
	v_max_f32_e32 v81, 0, v81
	v_max_f32_e32 v82, 0, v82
	v_lshl_add_u64 v[96:97], v[174:175], 0, v[96:97]
	v_cvt_pk_bf16_f32 v89, v89, v90
	v_cvt_pk_bf16_f32 v90, v98, v93
	v_cvt_pk_bf16_f32 v91, v94, v91
	v_max_f32_e32 v84, 0, v84
	global_store_dwordx4 v[96:97], v[88:91], off
	s_nop 1
	v_mul_f32_e32 v88, v80, v80
	v_max_f32_e32 v80, 0, v85
	v_mul_f32_e32 v85, v81, v81
	v_max_f32_e32 v81, 0, v86
	v_mul_f32_e32 v86, v82, v82
	v_max_f32_e32 v82, 0, v87
	v_mul_f32_e32 v80, v80, v80
	v_mul_f32_e32 v81, v81, v81
	v_max_f32_e32 v83, 0, v83
	v_mul_f32_e32 v82, v82, v82
	v_pk_mul_f32 v[72:73], v[154:155], v[72:73] op_sel_hi:[0,1]
	v_mul_f32_e32 v84, v84, v84
	v_mul_f32_e32 v83, v83, v83
	v_cvt_pk_bf16_f32 v80, v84, v80
	v_cvt_pk_bf16_f32 v81, v81, v82
	v_cvt_pk_bf16_f32 v82, v88, v85
	v_pk_mul_f32 v[76:77], v[154:155], v[76:77] op_sel_hi:[0,1]
	v_pk_mul_f32 v[74:75], v[154:155], v[74:75] op_sel_hi:[0,1]
	v_max_f32_e32 v72, 0, v72
	v_cvt_pk_bf16_f32 v83, v86, v83
	v_lshl_add_u64 v[84:85], v[96:97], 0, s[22:23]
	global_store_dwordx4 v[84:85], v[80:83], off
	s_nop 1
	v_or_b32_e32 v80, 48, v172
	v_pk_mul_f32 v[78:79], v[154:155], v[78:79] op_sel_hi:[0,1]
	v_mul_f32_e32 v82, v72, v72
	v_max_f32_e32 v72, 0, v77
	v_max_f32_e32 v73, 0, v73
	v_max_f32_e32 v74, 0, v74
	v_ashrrev_i32_e32 v81, 31, v80
	v_max_f32_e32 v76, 0, v76
	v_mul_f32_e32 v72, v72, v72
	v_mul_f32_e32 v77, v73, v73
	v_max_f32_e32 v73, 0, v78
	v_mul_f32_e32 v78, v74, v74
	v_max_f32_e32 v74, 0, v79
	v_max_f32_e32 v75, 0, v75
	v_pk_mul_f32 v[66:67], v[154:155], v[66:67] op_sel_hi:[0,1]
	v_pk_mul_f32 v[64:65], v[154:155], v[64:65] op_sel_hi:[0,1]
	v_lshlrev_b64 v[80:81], 14, v[80:81]
	v_mul_f32_e32 v76, v76, v76
	v_mul_f32_e32 v73, v73, v73
	v_mul_f32_e32 v74, v74, v74
	v_mul_f32_e32 v75, v75, v75
	v_cvt_pk_bf16_f32 v72, v76, v72
	v_pk_mul_f32 v[70:71], v[154:155], v[70:71] op_sel_hi:[0,1]
	v_pk_mul_f32 v[68:69], v[154:155], v[68:69] op_sel_hi:[0,1]
	v_max_f32_e32 v64, 0, v64
	v_max_f32_e32 v65, 0, v65
	v_max_f32_e32 v66, 0, v66
	v_lshl_add_u64 v[80:81], v[174:175], 0, v[80:81]
	v_cvt_pk_bf16_f32 v73, v73, v74
	v_cvt_pk_bf16_f32 v74, v82, v77
	v_cvt_pk_bf16_f32 v75, v78, v75
	v_max_f32_e32 v68, 0, v68
	global_store_dwordx4 v[80:81], v[72:75], off
	s_nop 1
	v_mul_f32_e32 v72, v64, v64
	v_max_f32_e32 v64, 0, v69
	v_mul_f32_e32 v69, v65, v65
	v_max_f32_e32 v65, 0, v70
	v_mul_f32_e32 v70, v66, v66
	v_max_f32_e32 v66, 0, v71
	v_mul_f32_e32 v64, v64, v64
	v_mul_f32_e32 v65, v65, v65
	v_max_f32_e32 v67, 0, v67
	v_mul_f32_e32 v66, v66, v66
	v_pk_mul_f32 v[56:57], v[152:153], v[56:57] op_sel_hi:[0,1]
	v_mul_f32_e32 v68, v68, v68
	v_mul_f32_e32 v67, v67, v67
	v_cvt_pk_bf16_f32 v64, v68, v64
	v_cvt_pk_bf16_f32 v65, v65, v66
	v_cvt_pk_bf16_f32 v66, v72, v69
	v_pk_mul_f32 v[60:61], v[152:153], v[60:61] op_sel_hi:[0,1]
	v_pk_mul_f32 v[58:59], v[152:153], v[58:59] op_sel_hi:[0,1]
	v_max_f32_e32 v56, 0, v56
	v_cvt_pk_bf16_f32 v67, v70, v67
	v_lshl_add_u64 v[68:69], v[80:81], 0, s[22:23]
	global_store_dwordx4 v[68:69], v[64:67], off
	s_nop 1
	v_pk_mul_f32 v[62:63], v[152:153], v[62:63] op_sel_hi:[0,1]
	v_mul_f32_e32 v66, v56, v56
	v_max_f32_e32 v56, 0, v61
	v_max_f32_e32 v57, 0, v57
	v_max_f32_e32 v58, 0, v58
	v_max_f32_e32 v60, 0, v60
	v_mul_f32_e32 v56, v56, v56
	v_mul_f32_e32 v61, v57, v57
	v_max_f32_e32 v57, 0, v62
	v_mul_f32_e32 v62, v58, v58
	v_max_f32_e32 v58, 0, v63
	v_max_f32_e32 v59, 0, v59
	v_pk_mul_f32 v[50:51], v[152:153], v[50:51] op_sel_hi:[0,1]
	v_pk_mul_f32 v[48:49], v[152:153], v[48:49] op_sel_hi:[0,1]
	v_mul_f32_e32 v60, v60, v60
	v_mul_f32_e32 v57, v57, v57
	v_mul_f32_e32 v58, v58, v58
	v_mul_f32_e32 v59, v59, v59
	v_cvt_pk_bf16_f32 v56, v60, v56
	v_pk_mul_f32 v[54:55], v[152:153], v[54:55] op_sel_hi:[0,1]
	v_pk_mul_f32 v[52:53], v[152:153], v[52:53] op_sel_hi:[0,1]
; __device__ __forceinline__ unsigned cvt_pk_bf16(float lo, float hi) { unsigned r; asm volatile("v_cvt_pk_bf16_f32 %0, %1, %2" : "=v"(r) : "v"(lo), "v"(hi)); return r; }
; #define PG8_BAR __builtin_amdgcn_s_barrier()
; template <class Epi, bool ALIGN_EPI>
; __device__ __forceinline__ void gemm_phase(LAS unsigned char* lds, const Gemm g, const StaticOrder& S, const Epi& E) {
;     ...
;         if (!has_next) break;
;         E.post(ui + 1, rsn);
; #pragma unroll
;         for (int a = 0; a < 2; ++a)
; #pragma unroll
;             for (int b = 0; b < 2; ++b)
; #pragma unroll
;                 for (int m = 0; m < 4; ++m)
; #pragma unroll
;                     for (int n = 0; n < 2; ++n) acc[a][b][m][n] = (f32x4){0.f, 0.f, 0.f, 0.f};
;         cur = nxt; cA = nA; cB = nB; ++ui;
; #pragma unroll
;         for (int i_ = 0; i_ < 8; ++i_) rsv[i_] = rsn[i_];
;         if constexpr (ALIGN_EPI) { if (wr == 1) PG8_BAR; }
;     __device__ __forceinline__ void operator()(const f32x4 (&acc)[2][2][4][2], const Unit& u, int wr, int wc, int fr, int fq, int, const float (&rsv_)[8]) const {
;     ...
;             for (int m = 0; m < 4; ++m) { bf16_t* rowp = base + (size_t)(row0 + ai * HALF + m * 16) * ldc + col0;
;                 const float rs = rsv[ai][m];
; #pragma unroll
;                 for (int bj = 0; bj < 2; ++bj) { f32x4 v0 = acc[ai][bj][m][0] * rs, v1 = acc[ai][bj][m][1] * rs;
;                     if (ACT == 1) {
; #pragma unroll
;                         for (int j = 0; j < 4; ++j) { const float a = fmaxf(v0[j], 0.f), b = fmaxf(v1[j], 0.f); v0[j] = a * a; v1[j] = b * b; } }
;                     if (ACT == 2) { if (act2) {
; #pragma unroll
;                         for (int j = 0; j < 4; ++j) { float x = v0[j]; float z = 0.7978845608028654f * (x + 0.044715f * x * x * x); v0[j] = x / (1.f + __expf(-2.f * z));
;                                                       x = v1[j]; z = 0.7978845608028654f * (x + 0.044715f * x * x * x); v1[j] = x / (1.f + __expf(-2.f * z)); } } }
;                     u32x4 w; w.x = cvt_pk_bf16(v0[0], v0[1]); w.y = cvt_pk_bf16(v0[2], v0[3]); w.z = cvt_pk_bf16(v1[0], v1[1]); w.w = cvt_pk_bf16(v1[2], v1[3]);
;                     { u32x4* dp_ = (u32x4*)(rowp + bj * HALF); asm volatile("global_store_dwordx4 %0, %1, off sc1\n\ts_nop 1" :: "v"(dp_), "v"(w) : "memory"); } } }
	v_max_f32_e32 v48, 0, v48
	v_max_f32_e32 v49, 0, v49
	v_max_f32_e32 v50, 0, v50
	v_lshl_add_u64 v[64:65], v[144:145], 0, s[24:25]
	v_cvt_pk_bf16_f32 v57, v57, v58
	v_cvt_pk_bf16_f32 v58, v66, v61
	v_cvt_pk_bf16_f32 v59, v62, v59
	v_max_f32_e32 v52, 0, v52
	global_store_dwordx4 v[64:65], v[56:59], off
	s_nop 1
	v_mul_f32_e32 v56, v48, v48
	v_max_f32_e32 v48, 0, v53
	v_mul_f32_e32 v53, v49, v49
	v_max_f32_e32 v49, 0, v54
	v_mul_f32_e32 v54, v50, v50
	v_max_f32_e32 v50, 0, v55
	v_mul_f32_e32 v48, v48, v48
	v_mul_f32_e32 v49, v49, v49
	v_max_f32_e32 v51, 0, v51
	v_mul_f32_e32 v50, v50, v50
	v_pk_mul_f32 v[40:41], v[150:151], v[40:41] op_sel_hi:[0,1]
	v_mul_f32_e32 v52, v52, v52
	v_mul_f32_e32 v51, v51, v51
	v_cvt_pk_bf16_f32 v48, v52, v48
	v_cvt_pk_bf16_f32 v49, v49, v50
	v_cvt_pk_bf16_f32 v50, v56, v53
	v_pk_mul_f32 v[44:45], v[150:151], v[44:45] op_sel_hi:[0,1]
	v_pk_mul_f32 v[42:43], v[150:151], v[42:43] op_sel_hi:[0,1]
	v_max_f32_e32 v40, 0, v40
	v_cvt_pk_bf16_f32 v51, v54, v51
	v_lshl_add_u64 v[52:53], v[144:145], 0, s[26:27]
	global_store_dwordx4 v[52:53], v[48:51], off
	s_nop 1
	v_pk_mul_f32 v[46:47], v[150:151], v[46:47] op_sel_hi:[0,1]
	v_mul_f32_e32 v50, v40, v40
	v_max_f32_e32 v40, 0, v45
	v_max_f32_e32 v41, 0, v41
	v_max_f32_e32 v42, 0, v42
	v_max_f32_e32 v44, 0, v44
	v_mul_f32_e32 v40, v40, v40
	v_mul_f32_e32 v45, v41, v41
	v_max_f32_e32 v41, 0, v46
	v_mul_f32_e32 v46, v42, v42
	v_max_f32_e32 v42, 0, v47
	v_max_f32_e32 v43, 0, v43
	v_pk_mul_f32 v[34:35], v[150:151], v[34:35] op_sel_hi:[0,1]
	v_pk_mul_f32 v[32:33], v[150:151], v[32:33] op_sel_hi:[0,1]
	v_mul_f32_e32 v44, v44, v44
	v_mul_f32_e32 v41, v41, v41
	v_mul_f32_e32 v42, v42, v42
	v_mul_f32_e32 v43, v43, v43
	v_cvt_pk_bf16_f32 v40, v44, v40
	v_pk_mul_f32 v[38:39], v[150:151], v[38:39] op_sel_hi:[0,1]
	v_pk_mul_f32 v[36:37], v[150:151], v[36:37] op_sel_hi:[0,1]
	v_max_f32_e32 v32, 0, v32
	v_max_f32_e32 v33, 0, v33
	v_max_f32_e32 v34, 0, v34
	v_lshl_add_u64 v[48:49], v[144:145], 0, s[28:29]
	v_cvt_pk_bf16_f32 v41, v41, v42
	v_cvt_pk_bf16_f32 v42, v50, v45
	v_cvt_pk_bf16_f32 v43, v46, v43
	v_max_f32_e32 v36, 0, v36
	global_store_dwordx4 v[48:49], v[40:43], off
	s_nop 1
	v_mul_f32_e32 v40, v32, v32
	v_max_f32_e32 v32, 0, v37
	v_mul_f32_e32 v37, v33, v33
	v_max_f32_e32 v33, 0, v38
	v_mul_f32_e32 v38, v34, v34
	v_max_f32_e32 v34, 0, v39
	v_mul_f32_e32 v32, v32, v32
	v_mul_f32_e32 v33, v33, v33
	v_max_f32_e32 v35, 0, v35
	v_mul_f32_e32 v34, v34, v34
	v_pk_mul_f32 v[24:25], v[148:149], v[24:25] op_sel_hi:[0,1]
	v_mul_f32_e32 v36, v36, v36
	v_mul_f32_e32 v35, v35, v35
	v_cvt_pk_bf16_f32 v32, v36, v32
	v_cvt_pk_bf16_f32 v33, v33, v34
	v_cvt_pk_bf16_f32 v34, v40, v37
	v_pk_mul_f32 v[28:29], v[148:149], v[28:29] op_sel_hi:[0,1]
	v_pk_mul_f32 v[26:27], v[148:149], v[26:27] op_sel_hi:[0,1]
	v_max_f32_e32 v24, 0, v24
	v_cvt_pk_bf16_f32 v35, v38, v35
	v_lshl_add_u64 v[36:37], v[144:145], 0, s[30:31]
	global_store_dwordx4 v[36:37], v[32:35], off
	s_nop 1
	v_pk_mul_f32 v[30:31], v[148:149], v[30:31] op_sel_hi:[0,1]
	v_mul_f32_e32 v34, v24, v24
	v_max_f32_e32 v24, 0, v29
	v_max_f32_e32 v25, 0, v25
	v_max_f32_e32 v26, 0, v26
	v_max_f32_e32 v28, 0, v28
	v_mul_f32_e32 v24, v24, v24
	v_mul_f32_e32 v29, v25, v25
	v_max_f32_e32 v25, 0, v30
	v_mul_f32_e32 v30, v26, v26
	v_max_f32_e32 v26, 0, v31
	v_max_f32_e32 v27, 0, v27
	v_pk_mul_f32 v[18:19], v[148:149], v[18:19] op_sel_hi:[0,1]
	v_pk_mul_f32 v[16:17], v[148:149], v[16:17] op_sel_hi:[0,1]
	v_mul_f32_e32 v28, v28, v28
	v_mul_f32_e32 v25, v25, v25
	v_mul_f32_e32 v26, v26, v26
	v_mul_f32_e32 v27, v27, v27
	v_cvt_pk_bf16_f32 v24, v28, v24
	v_pk_mul_f32 v[22:23], v[148:149], v[22:23] op_sel_hi:[0,1]
	v_pk_mul_f32 v[20:21], v[148:149], v[20:21] op_sel_hi:[0,1]
	v_max_f32_e32 v16, 0, v16
	v_max_f32_e32 v17, 0, v17
	v_max_f32_e32 v18, 0, v18
	v_lshl_add_u64 v[32:33], v[144:145], 0, s[34:35]
	v_cvt_pk_bf16_f32 v25, v25, v26
	v_cvt_pk_bf16_f32 v26, v34, v29
	v_cvt_pk_bf16_f32 v27, v30, v27
	v_max_f32_e32 v20, 0, v20
	global_store_dwordx4 v[32:33], v[24:27], off
	s_nop 1
	v_mul_f32_e32 v24, v16, v16
	v_max_f32_e32 v16, 0, v21
	v_mul_f32_e32 v21, v17, v17
	v_max_f32_e32 v17, 0, v22
	v_mul_f32_e32 v22, v18, v18
	v_max_f32_e32 v18, 0, v23
	v_mul_f32_e32 v16, v16, v16
	v_mul_f32_e32 v17, v17, v17
	v_max_f32_e32 v19, 0, v19
	v_mul_f32_e32 v18, v18, v18
	v_pk_mul_f32 v[8:9], v[146:147], v[8:9] op_sel_hi:[0,1]
	v_mul_f32_e32 v20, v20, v20
	v_mul_f32_e32 v19, v19, v19
	v_cvt_pk_bf16_f32 v16, v20, v16
	v_cvt_pk_bf16_f32 v17, v17, v18
	v_cvt_pk_bf16_f32 v18, v24, v21
	v_pk_mul_f32 v[12:13], v[146:147], v[12:13] op_sel_hi:[0,1]
	v_pk_mul_f32 v[10:11], v[146:147], v[10:11] op_sel_hi:[0,1]
	v_max_f32_e32 v8, 0, v8
	v_cvt_pk_bf16_f32 v19, v22, v19
	v_lshl_add_u64 v[20:21], v[144:145], 0, s[36:37]
	global_store_dwordx4 v[20:21], v[16:19], off
	s_nop 1
	v_pk_mul_f32 v[14:15], v[146:147], v[14:15] op_sel_hi:[0,1]
	v_mul_f32_e32 v18, v8, v8
	v_max_f32_e32 v8, 0, v13
	v_max_f32_e32 v9, 0, v9
	v_max_f32_e32 v10, 0, v10
	v_max_f32_e32 v12, 0, v12
	v_mul_f32_e32 v8, v8, v8
	v_mul_f32_e32 v13, v9, v9
	v_max_f32_e32 v9, 0, v14
	v_mul_f32_e32 v14, v10, v10
	v_max_f32_e32 v10, 0, v15
	v_max_f32_e32 v11, 0, v11
	v_pk_mul_f32 v[2:3], v[146:147], v[2:3] op_sel_hi:[0,1]
	v_pk_mul_f32 v[0:1], v[146:147], v[0:1] op_sel_hi:[0,1]
	v_mul_f32_e32 v12, v12, v12
	v_mul_f32_e32 v9, v9, v9
	v_mul_f32_e32 v10, v10, v10
	v_mul_f32_e32 v11, v11, v11
	v_cvt_pk_bf16_f32 v8, v12, v8
	v_pk_mul_f32 v[6:7], v[146:147], v[6:7] op_sel_hi:[0,1]
	v_pk_mul_f32 v[4:5], v[146:147], v[4:5] op_sel_hi:[0,1]
	v_max_f32_e32 v0, 0, v0
	v_max_f32_e32 v1, 0, v1
	v_max_f32_e32 v2, 0, v2
	v_lshl_add_u64 v[16:17], v[144:145], 0, s[40:41]
	v_cvt_pk_bf16_f32 v9, v9, v10
	v_cvt_pk_bf16_f32 v10, v18, v13
	v_cvt_pk_bf16_f32 v11, v14, v11
	v_max_f32_e32 v4, 0, v4
	global_store_dwordx4 v[16:17], v[8:11], off
	s_nop 1
	v_mul_f32_e32 v8, v0, v0
	v_max_f32_e32 v0, 0, v5
	v_mul_f32_e32 v5, v1, v1
	v_max_f32_e32 v1, 0, v6
	v_mul_f32_e32 v6, v2, v2
	v_max_f32_e32 v2, 0, v7
	v_max_f32_e32 v3, 0, v3
	v_mul_f32_e32 v4, v4, v4
	v_mul_f32_e32 v0, v0, v0
	v_mul_f32_e32 v1, v1, v1
	v_mul_f32_e32 v2, v2, v2
	v_mul_f32_e32 v3, v3, v3
	v_cvt_pk_bf16_f32 v0, v4, v0
	v_cvt_pk_bf16_f32 v1, v1, v2
	v_cvt_pk_bf16_f32 v2, v8, v5
	v_cvt_pk_bf16_f32 v3, v6, v3
	v_lshl_add_u64 v[4:5], v[144:145], 0, s[42:43]
	global_store_dwordx4 v[4:5], v[0:3], off
	s_nop 1
	s_and_b64 vcc, exec, s[6:7]
	s_mov_b64 s[4:5], -1
	s_cbranch_vccnz .LBB0_918
	s_andn2_b64 vcc, exec, s[14:15]
	s_cbranch_vccnz .LBB0_917
	s_barrier
	s_branch .LBB0_917
